# grid barrier: completing leader bumps every XCD generation word itself (no relay through other leaders)
# speedup vs baseline: 1.0088x; 1.0035x over previous
.LBB0_388:
	v_readlane_b32 s44, v249, 0
	v_readlane_b32 s45, v249, 1
	s_add_u32 s59, s44, 0x20e00000
	s_addc_u32 s60, s45, 0
	s_add_u32 s0, s44, 0x22200000
	s_addc_u32 s69, s45, 0
	v_writelane_b32 v250, s0, 41
	s_add_u32 s0, s44, 0x23600000
	s_addc_u32 s1, s45, 0
	v_writelane_b32 v250, s0, 13
	v_readlane_b32 s30, v249, 8
	v_readlane_b32 s34, v249, 6
	v_writelane_b32 v250, s1, 14
	s_add_u32 s0, s44, 0x24a00000
	s_addc_u32 s1, s45, 0
	v_writelane_b32 v250, s0, 38
	s_mov_b32 s29, 0
	v_mov_b32_e32 v1, 0x2800
	v_writelane_b32 v250, s1, 39
	s_add_u32 s0, s44, 0x25e00000
	s_addc_u32 s1, s45, 0
	v_writelane_b32 v250, s0, 50
	v_mov_b32_e32 v3, 0x2c00
	v_mov_b32_e32 v5, 0x3400
	v_writelane_b32 v250, s1, 51
	s_add_u32 s0, s44, 0x27200000
	s_addc_u32 s1, s45, 0
	v_writelane_b32 v250, s0, 63
	v_readlane_b32 s46, v249, 2
	v_readlane_b32 s47, v249, 3
	v_writelane_b32 v251, s1, 0
	s_add_u32 s0, s44, 0x29a00000
	s_addc_u32 s1, s45, 0
	s_add_u32 s64, s44, 0x2c200000
	s_addc_u32 s65, s45, 0
	s_add_u32 s40, s44, 0x2ea00000
	s_addc_u32 s41, s45, 0
	s_add_u32 s42, s44, 0x31200000
	s_addc_u32 s43, s45, 0
	s_add_u32 s48, s44, 0x3b200000
	s_addc_u32 s49, s45, 0
	v_writelane_b32 v251, s0, 1
	s_cmpk_gt_i32 s30, 0xef
	v_readlane_b32 s46, v249, 9
	v_writelane_b32 v251, s1, 2
	s_cselect_b64 s[0:1], -1, 0
	s_cmpk_eq_i32 s34, 0x100
	s_cselect_b64 s[6:7], -1, 0
	s_and_b64 s[2:3], s[6:7], exec
	s_cselect_b32 s31, 32, 40
	s_and_b64 s[0:1], s[0:1], s[6:7]
	v_writelane_b32 v251, s0, 3
	s_add_i32 s28, s30, 0xffffff10
	v_readlane_b32 s35, v249, 7
	v_writelane_b32 v251, s1, 4
	s_add_u32 s0, s44, 0x1d400000
	v_writelane_b32 v251, s0, 5
	s_addc_u32 s0, s45, 0
	v_writelane_b32 v251, s0, 6
	s_lshl_b64 s[0:1], s[28:29], 12
	v_writelane_b32 v251, s0, 7
	s_mov_b32 s70, 0xfff3fff0
	s_mov_b32 s74, 0xfff7fff0
	v_writelane_b32 v251, s1, 8
	s_add_u32 s0, s44, 0x1dc00000
	v_writelane_b32 v251, s0, 9
	s_addc_u32 s0, s45, 0
	v_writelane_b32 v251, s0, 10
	s_lshl_b32 s0, s28, 3
	s_add_i32 s3, s57, s0
	s_lshl_b32 s2, s57, 14
	s_add_i32 s8, s3, 0x2400
	s_add_i32 s68, s2, 0
	s_cmpk_lt_i32 s8, 0x4b80
	s_cselect_b64 s[10:11], -1, 0
	v_writelane_b32 v251, s10, 11
	s_cmpk_lt_i32 s8, 0x2400
	v_sub_co_u32_e32 v2, vcc, s8, v1
	v_writelane_b32 v251, s11, 12
	s_cselect_b64 s[10:11], -1, 0
	v_writelane_b32 v251, s10, 13
	s_cmpk_gt_i32 s8, 0x23ff
	v_sub_co_u32_e64 v4, s[0:1], s8, v3
	v_writelane_b32 v251, s11, 14
	s_cselect_b64 s[10:11], -1, 0
	v_writelane_b32 v251, s10, 15
	s_xor_b64 s[0:1], s[0:1], -1
	s_waitcnt vmcnt(10)
	v_sub_co_u32_e64 v6, s[4:5], s8, v5
	v_writelane_b32 v251, s11, 16
	s_xor_b64 s[10:11], vcc, -1
	v_writelane_b32 v251, s10, 17
	v_readfirstlane_b32 s2, v2
	s_mov_b32 s94, 0xfffbfff0
	v_writelane_b32 v251, s11, 18
	v_writelane_b32 v251, s0, 19
	s_mov_b64 s[62:63], 0x80000
	s_mov_b32 s71, -1
	v_writelane_b32 v251, s1, 20
	s_xor_b64 s[0:1], s[4:5], -1
	v_writelane_b32 v251, s0, 21
	s_mov_b64 s[72:73], 0x70000
	s_mov_b32 s75, -1
	v_writelane_b32 v251, s1, 22
	s_add_u32 s0, s44, 0xd400000
	v_writelane_b32 v251, s0, 23
	s_addc_u32 s0, s45, 0
	v_writelane_b32 v251, s0, 24
	s_add_u32 s0, s44, 0xb400000
	v_writelane_b32 v251, s0, 25
	s_addc_u32 s0, s45, 0
	v_writelane_b32 v251, s0, 26
	s_add_u32 s0, s44, 0x9400000
	v_writelane_b32 v251, s0, 27
	s_addc_u32 s0, s45, 0
	v_writelane_b32 v251, s0, 28
	s_add_u32 s0, s44, 0x400000
	v_writelane_b32 v251, s0, 29
	s_addc_u32 s0, s45, 0
	v_writelane_b32 v251, s0, 30
	s_add_i32 s0, s3, 0x2480
	s_cmpk_lt_i32 s8, 0x4b00
	s_cselect_b64 s[4:5], -1, 0
	v_writelane_b32 v251, s4, 31
	s_cmpk_lt_i32 s8, 0x2380
	s_mov_b64 s[92:93], 0x60000
	v_writelane_b32 v251, s5, 32
	s_cselect_b64 s[4:5], -1, 0
	v_writelane_b32 v251, s4, 33
	s_cmpk_gt_i32 s8, 0x237f
	s_mov_b32 s95, -1
	v_writelane_b32 v251, s5, 34
	s_cselect_b64 s[4:5], -1, 0
	v_writelane_b32 v251, s4, 35
	s_cmpk_gt_u32 s0, 0x27ff
	s_mov_b64 s[96:97], 0x50000
	v_writelane_b32 v251, s5, 36
	s_cselect_b64 s[4:5], -1, 0
	v_writelane_b32 v251, s4, 37
	s_cmpk_gt_u32 s0, 0x2bff
	s_mov_b32 s58, 0x20000
	v_writelane_b32 v251, s5, 38
	s_cselect_b64 s[4:5], -1, 0
	v_writelane_b32 v251, s4, 39
	s_cmpk_gt_u32 s0, 0x33ff
	v_mov_b32_e32 v201, 0xc0135761
	v_writelane_b32 v251, s5, 40
	v_writelane_b32 v251, s0, 41
	s_cselect_b64 s[0:1], -1, 0
	v_writelane_b32 v251, s0, 42
	v_mov_b32_e32 v202, 1
	v_mov_b32_e32 v203, 0x358637bd
	v_writelane_b32 v251, s1, 43
	s_add_i32 s0, s3, 0xfffff080
	v_writelane_b32 v251, s0, 44
	s_add_i32 s0, s3, 0xfffff880
	v_writelane_b32 v251, s0, 45
	s_add_i32 s0, s3, 0xfffffc80
	v_writelane_b32 v251, s0, 46
	s_add_i32 s0, s3, 0x80
	v_writelane_b32 v251, s0, 47
	s_add_i32 s0, s3, 0x2500
	s_cmpk_lt_i32 s8, 0x4a80
	s_cselect_b64 s[4:5], -1, 0
	v_writelane_b32 v251, s4, 48
	s_cmpk_lt_i32 s8, 0x2300
	v_mov_b64_e32 v[168:169], 0x5a0
	v_writelane_b32 v251, s5, 49
	s_cselect_b64 s[4:5], -1, 0
	v_writelane_b32 v251, s4, 50
	s_cmpk_gt_i32 s8, 0x22ff
	v_mov_b64_e32 v[170:171], 0x59f
	v_writelane_b32 v251, s5, 51
	v_writelane_b32 v251, s8, 52
	s_cselect_b64 s[4:5], -1, 0
	v_writelane_b32 v251, s4, 53
	s_cmpk_gt_u32 s0, 0x27ff
	v_readlane_b32 s8, v249, 43
	v_writelane_b32 v251, s5, 54
	s_cselect_b64 s[4:5], -1, 0
	v_writelane_b32 v251, s4, 55
	s_cmpk_gt_u32 s0, 0x2bff
	v_readlane_b32 s9, v249, 44
	v_writelane_b32 v251, s5, 56
	s_cselect_b64 s[4:5], -1, 0
	v_writelane_b32 v251, s4, 57
	s_cmpk_gt_u32 s0, 0x33ff
	v_mov_b64_e32 v[172:173], 0x140
	v_writelane_b32 v251, s5, 58
	v_writelane_b32 v251, s0, 59
	s_cselect_b64 s[0:1], -1, 0
	v_writelane_b32 v251, s0, 60
	v_mov_b64_e32 v[174:175], 0x13f
	v_mov_b32_e32 v205, 0xc000
	v_writelane_b32 v251, s1, 61
	s_add_i32 s0, s3, 0xfffff100
	v_writelane_b32 v251, s0, 62
	s_add_i32 s0, s3, 0xfffff900
	v_writelane_b32 v251, s0, 63
	s_add_i32 s0, s3, 0xfffffd00
	v_writelane_b32 v252, s0, 0
	s_add_i32 s0, s3, 0x100
	s_add_u32 s66, s44, 0x1e400000
	v_writelane_b32 v252, s3, 1
	s_addc_u32 s67, s45, 0
	v_writelane_b32 v252, s0, 2
	s_add_u32 s0, s44, 0x100000
	s_addc_u32 s1, s45, 0
	v_writelane_b32 v252, s0, 3
	s_cmpk_lt_i32 s30, 0x5a0
	v_mov_b32_e32 v206, 0x3a000000
	v_writelane_b32 v252, s1, 4
	s_cselect_b64 s[0:1], -1, 0
	v_writelane_b32 v252, s0, 5
	v_mov_b64_e32 v[176:177], 0x500
	v_mov_b64_e32 v[178:179], 0x4ff
	v_writelane_b32 v252, s1, 6
	s_ashr_i32 s0, s30, 31
	v_writelane_b32 v250, s0, 28
	s_lshr_b32 s0, s0, 29
	s_add_i32 s0, s30, s0
	s_ashr_i32 s3, s0, 3
	s_and_b32 s0, s0, -8
	s_sub_i32 s4, s30, s0
	v_writelane_b32 v252, s2, 7
	v_readfirstlane_b32 s2, v4
	s_cmpk_lg_i32 s34, 0x100
	s_cselect_b64 s[0:1], -1, 0
	v_writelane_b32 v252, s2, 8
	v_readfirstlane_b32 s2, v6
	v_writelane_b32 v250, s6, 19
	v_mov_b32_e32 v4, 0x5400
	v_writelane_b32 v252, s2, 9
	v_writelane_b32 v252, s0, 10
	v_writelane_b32 v250, s7, 20
	s_mov_b32 s54, s29
	v_writelane_b32 v252, s1, 11
	s_and_b64 s[0:1], s[0:1], exec
	s_cselect_b32 s0, s34, 0xf0
	s_cselect_b32 s14, s34, 0xa0
	v_writelane_b32 v252, s0, 12
	s_ashr_i32 s0, s0, 31
	v_writelane_b32 v252, s0, 13
	s_add_u32 s0, s44, 0x4200
	s_addc_u32 s1, s45, 0
	v_writelane_b32 v252, s0, 14
	v_readlane_b32 s47, v249, 10
	s_nop 0
	v_writelane_b32 v252, s1, 15
	s_add_u32 s0, s44, 0x4400
	s_addc_u32 s1, s45, 0
	v_writelane_b32 v252, s0, 16
	s_nop 1
	v_writelane_b32 v252, s1, 17
	s_add_u32 s0, s44, 0x4500
	s_addc_u32 s1, s45, 0
	v_writelane_b32 v252, s0, 18
	s_nop 1
	v_writelane_b32 v252, s1, 19
	s_add_u32 s0, s44, 0x4600
	s_addc_u32 s1, s45, 0
	v_writelane_b32 v252, s0, 20
	s_nop 1
	v_writelane_b32 v252, s1, 21
	s_add_u32 s0, s44, 0x4700
	s_addc_u32 s1, s45, 0
	v_writelane_b32 v252, s0, 22
	s_nop 1
	v_writelane_b32 v252, s1, 23
	s_add_u32 s0, s44, 0x4800
	s_addc_u32 s1, s45, 0
	v_writelane_b32 v252, s0, 24
	s_nop 1
	v_writelane_b32 v252, s1, 25
	s_add_u32 s0, s44, 0x4900
	s_addc_u32 s1, s45, 0
	v_writelane_b32 v252, s0, 26
	s_nop 1
	v_writelane_b32 v252, s1, 27
	s_add_u32 s0, s44, 0x4a00
	s_addc_u32 s1, s45, 0
	v_writelane_b32 v252, s0, 28
	s_nop 1
	v_writelane_b32 v252, s1, 29
	s_add_u32 s0, s44, 0x4b00
	s_addc_u32 s1, s45, 0
	v_writelane_b32 v252, s0, 30
	s_nop 1
	v_writelane_b32 v252, s1, 31
	s_add_u32 s0, s44, 0x4c00
	s_addc_u32 s1, s45, 0
	v_writelane_b32 v252, s0, 32
	s_nop 1
	v_writelane_b32 v252, s1, 33
	s_add_u32 s0, s44, 0x4d00
	s_addc_u32 s1, s45, 0
	v_writelane_b32 v252, s0, 34
	s_nop 1
	v_writelane_b32 v252, s1, 35
	s_add_u32 s0, s44, 0x4e00
	s_addc_u32 s1, s45, 0
	v_writelane_b32 v252, s0, 36
	s_nop 1
	v_writelane_b32 v252, s1, 37
	s_add_u32 s0, s44, 0x4f00
	s_addc_u32 s1, s45, 0
	v_writelane_b32 v252, s0, 38
	s_nop 1
	v_writelane_b32 v252, s1, 39
	s_add_u32 s0, s44, 0x5000
	s_addc_u32 s1, s45, 0
	v_writelane_b32 v252, s0, 40
	s_nop 1
	v_writelane_b32 v252, s1, 41
	s_add_u32 s0, s44, 0x5100
	s_addc_u32 s1, s45, 0
	v_writelane_b32 v252, s0, 42
	s_nop 1
	v_writelane_b32 v252, s1, 43
	s_add_u32 s0, s44, 0x5200
	s_addc_u32 s1, s45, 0
	v_writelane_b32 v252, s0, 44
	s_nop 1
	v_writelane_b32 v252, s1, 45
	s_add_u32 s0, s44, 0x5300
	s_addc_u32 s1, s45, 0
	v_writelane_b32 v252, s0, 46
	s_cmp_eq_u32 s56, 15
	s_nop 0
	v_writelane_b32 v252, s1, 47
	s_cselect_b64 s[0:1], -1, 0
	v_writelane_b32 v252, s0, 48
	s_cmp_eq_u32 s56, 14
	s_nop 0
	v_writelane_b32 v252, s1, 49
	s_cselect_b64 s[0:1], -1, 0
	v_writelane_b32 v252, s0, 50
	s_cmp_eq_u32 s56, 13
	s_nop 0
	v_writelane_b32 v252, s1, 51
	s_cselect_b64 s[0:1], -1, 0
	v_writelane_b32 v252, s0, 52
	s_cmp_eq_u32 s56, 12
	s_nop 0
	v_writelane_b32 v252, s1, 53
	s_cselect_b64 s[0:1], -1, 0
	v_writelane_b32 v252, s0, 54
	s_cmp_eq_u32 s56, 11
	s_nop 0
	v_writelane_b32 v252, s1, 55
	s_cselect_b64 s[0:1], -1, 0
	v_writelane_b32 v252, s0, 56
	s_cmp_eq_u32 s56, 10
	s_nop 0
	v_writelane_b32 v252, s1, 57
	s_cselect_b64 s[0:1], -1, 0
	v_writelane_b32 v252, s0, 58
	s_cmp_eq_u32 s56, 9
	s_nop 0
	v_writelane_b32 v252, s1, 59
	s_cselect_b64 s[0:1], -1, 0
	v_writelane_b32 v252, s0, 60
	s_cmp_eq_u32 s56, 8
	s_nop 0
	v_writelane_b32 v252, s1, 61
	s_cselect_b64 s[0:1], -1, 0
	v_writelane_b32 v252, s0, 62
	s_cmp_eq_u32 s56, 7
	s_nop 0
	v_writelane_b32 v252, s1, 63
	s_cselect_b64 s[0:1], -1, 0
	v_writelane_b32 v248, s0, 0
	s_cmp_eq_u32 s56, 6
	s_nop 0
	v_writelane_b32 v248, s1, 1
	s_cselect_b64 s[0:1], -1, 0
	v_writelane_b32 v248, s0, 2
	s_cmp_eq_u32 s56, 5
	s_nop 0
	v_writelane_b32 v248, s1, 3
	s_cselect_b64 s[0:1], -1, 0
	v_writelane_b32 v248, s0, 4
	s_cmp_eq_u32 s56, 4
	s_nop 0
	v_writelane_b32 v248, s1, 5
	s_cselect_b64 s[0:1], -1, 0
	v_writelane_b32 v248, s0, 6
	s_cmp_eq_u32 s56, 3
	s_nop 0
	v_writelane_b32 v248, s1, 7
	s_cselect_b64 s[0:1], -1, 0
	v_writelane_b32 v248, s0, 8
	s_cmp_eq_u32 s56, 2
	s_nop 0
	v_writelane_b32 v248, s1, 9
	s_cselect_b64 s[0:1], -1, 0
	v_writelane_b32 v248, s0, 10
	s_cmp_eq_u32 s56, 1
	s_nop 0
	v_writelane_b32 v248, s1, 11
	s_cselect_b64 s[0:1], -1, 0
	v_writelane_b32 v248, s0, 12
	s_cmp_eq_u32 s56, 0
	s_nop 0
	v_writelane_b32 v248, s1, 13
	s_cselect_b64 s[0:1], -1, 0
	v_writelane_b32 v248, s0, 14
	s_nop 1
	v_writelane_b32 v248, s1, 15
	s_lshl_b32 s0, s56, 8
	s_add_u32 s0, s8, s0
	s_addc_u32 s2, s9, 0
	s_add_u32 s8, s0, 0x1400
	s_addc_u32 s9, s2, 0
	v_writelane_b32 v248, s8, 16
	s_mul_i32 s1, s57, 0x1200
	s_nop 0
	v_writelane_b32 v248, s9, 17
	s_add_u32 s8, s0, 0x2400
	s_addc_u32 s9, s2, 0
	v_writelane_b32 v248, s8, 18
	s_nop 1
	v_writelane_b32 v248, s9, 19
	s_add_u32 s8, s44, 0x7400
	s_addc_u32 s9, s45, 0
	v_writelane_b32 v248, s8, 20
	s_nop 1
	v_writelane_b32 v248, s9, 21
	s_add_u32 s8, s44, 0x7500
	s_addc_u32 s9, s45, 0
	s_add_u32 s61, s44, 0x300000
	s_addc_u32 s33, s45, 0
	v_writelane_b32 v248, s8, 22
	s_cmpk_lt_i32 s46, 0x100
	s_nop 0
	v_writelane_b32 v248, s9, 23
	s_cselect_b64 s[8:9], -1, 0
	v_writelane_b32 v248, s8, 24
	s_add_i32 s0, s1, 0
	s_lshl_b32 s35, s57, 5
	v_writelane_b32 v248, s9, 25
	s_add_i32 s0, s0, 0x12000
	v_writelane_b32 v248, s0, 26
	s_add_u32 s0, s90, 0x5000000
	v_writelane_b32 v248, s0, 27
	s_addc_u32 s0, s91, 0
	s_cmpk_gt_i32 s30, 0x9f
	v_writelane_b32 v248, s0, 28
	s_cselect_b64 s[0:1], -1, 0
	s_and_b64 s[0:1], s[0:1], s[6:7]
	v_writelane_b32 v248, s0, 29
	v_readlane_b32 s8, v249, 46
	s_nop 0
	v_writelane_b32 v248, s1, 30
	s_lshl_b32 s0, s30, 3
	s_add_i32 s2, s57, s0
	s_add_i32 s5, s2, 0x4680
	s_cmpk_lt_i32 s5, 0x7400
	s_cselect_b64 s[6:7], -1, 0
	v_writelane_b32 v248, s6, 31
	s_cmpk_lt_i32 s5, 0x2400
	v_sub_co_u32_e32 v1, vcc, s5, v1
	v_writelane_b32 v248, s7, 32
	s_cselect_b64 s[6:7], -1, 0
	v_writelane_b32 v248, s6, 33
	s_cmpk_gt_i32 s5, 0x23ff
	v_sub_co_u32_e64 v2, s[0:1], s5, v3
	v_writelane_b32 v248, s7, 34
	v_writelane_b32 v248, s5, 35
	s_cselect_b64 s[6:7], -1, 0
	v_writelane_b32 v248, s6, 36
	s_xor_b64 s[0:1], s[0:1], -1
	v_sub_co_u32_e64 v3, s[36:37], s5, v5
	v_writelane_b32 v248, s7, 37
	s_xor_b64 s[6:7], vcc, -1
	v_writelane_b32 v248, s6, 38
	v_sub_co_u32_e64 v4, s[38:39], s5, v4
	s_nop 0
	v_writelane_b32 v248, s7, 39
	v_writelane_b32 v248, s0, 40
	s_nop 1
	v_writelane_b32 v248, s1, 41
	s_xor_b64 s[0:1], s[36:37], -1
	v_writelane_b32 v248, s0, 42
	s_nop 1
	v_writelane_b32 v248, s1, 43
	s_xor_b64 s[0:1], s[38:39], -1
	v_writelane_b32 v248, s0, 44
	s_mov_b32 s39, s29
	s_nop 0
	v_writelane_b32 v248, s1, 45
	s_add_u32 s0, s44, 0x15400000
	v_writelane_b32 v248, s0, 46
	s_addc_u32 s0, s45, 0
	v_writelane_b32 v248, s0, 47
	s_add_i32 s0, s2, 0x2280
	s_add_i32 s36, s2, 0xfffffb00
	v_writelane_b32 v248, s0, 48
	s_mul_hi_i32 s0, s36, 0x38e38e39
	s_cmpk_lt_i32 s36, 0x2400
	s_cselect_b64 s[6:7], -1, 0
	s_lshr_b32 s1, s0, 31
	s_ashr_i32 s5, s0, 6
	s_add_i32 s5, s5, s1
	s_mul_i32 s9, s5, 0xfffffee0
	s_add_i32 s9, s9, s36
	s_lshl_b32 s0, s9, 5
	s_cmpk_gt_u32 s9, 0xdf
	s_movk_i32 s1, 0xe400
	v_writelane_b32 v248, s6, 49
	s_cselect_b32 s1, s1, 0xffffec00
	s_nop 0
	v_writelane_b32 v248, s7, 50
	s_cselect_b32 s6, 0x80, 0
	s_add_i32 s1, s1, s0
	s_lshl_b32 s1, s1, 1
	s_and_b32 s1, s1, 0xffffff00
	s_or_b32 s1, s1, s6
	s_and_b32 s6, s0, 0x60
	s_or_b32 s10, s1, s6
	s_lshl_b32 s6, s5, 6
	s_addk_i32 s10, 0x1400
	s_ashr_i32 s7, s6, 31
	s_ashr_i32 s1, s0, 31
	s_cmpk_lt_i32 s36, 0x1000
	s_cselect_b64 s[12:13], -1, 0
	v_writelane_b32 v248, s12, 51
	s_mul_i32 s5, s5, 0x240000
	s_nop 0
	v_writelane_b32 v248, s13, 52
	s_ashr_i32 s12, s36, 7
	s_bitcmp0_b32 s8, 8
	s_mov_b32 s8, 0x24a00000
	s_cselect_b32 s8, s8, 0x25e00000
	s_add_u32 s8, s44, s8
	s_addc_u32 s11, s45, 0
	s_ashr_i32 s13, s12, 31
	s_lshl_b64 s[12:13], s[12:13], 19
	s_add_u32 s8, s8, s12
	s_addc_u32 s11, s11, s13
	s_lshl_b32 s12, s57, 17
	s_and_b32 s12, s12, 0x60000
	s_add_u32 s8, s8, s12
	s_addc_u32 s11, s11, 0
	s_lshl_b32 s12, s36, 3
	v_writelane_b32 v248, s12, 53
	s_lshl_b32 s12, s36, 4
	s_and_b32 s12, s12, 0x780
	s_add_u32 s12, s8, s12
	s_addc_u32 s13, s11, 0
	v_writelane_b32 v248, s12, 54
	s_cmpk_lt_i32 s30, 0x140
	s_nop 0
	v_writelane_b32 v248, s13, 55
	s_cselect_b64 s[12:13], -1, 0
	v_writelane_b32 v248, s12, 56
	s_ashr_i32 s8, s14, 31
	s_lshl_b32 s38, s31, 3
	v_writelane_b32 v248, s13, 57
	v_writelane_b32 v248, s14, 58
	s_cmp_lt_i32 s30, s38
	v_writelane_b32 v248, s8, 59
	s_cselect_b64 s[12:13], -1, 0
	s_ashr_i32 s8, s34, 31
	v_writelane_b32 v250, s8, 35
	s_ashr_i32 s8, s46, 5
	s_add_i32 s8, s8, 32
	v_writelane_b32 v250, s8, 34
	s_bfe_u32 s8, s46, 0x30002
	s_lshl_b32 s26, s46, 3
	v_writelane_b32 v248, s12, 60
	s_or_b32 s11, s31, 1
	v_writelane_b32 v250, s8, 37
	s_and_b32 s8, s26, 24
	v_writelane_b32 v248, s13, 61
	s_cmpk_lt_i32 s46, 0x500
	v_writelane_b32 v248, s8, 62
	s_cselect_b64 s[12:13], -1, 0
	s_add_u32 s50, s44, 0x45200000
	v_writelane_b32 v248, s12, 63
	s_addc_u32 s51, s45, 0
	s_ashr_i32 s27, s26, 31
	v_writelane_b32 v247, s13, 0
	s_lshl_b32 s8, s57, 8
	s_lshl_b64 s[12:13], s[26:27], 12
	s_add_u32 s14, s50, s12
	v_writelane_b32 v247, s8, 1
	s_addc_u32 s15, s51, s13
	v_writelane_b32 v247, s14, 2
	s_mov_b32 s8, s26
	s_mov_b64 s[56:57], 0x40000
	v_writelane_b32 v247, s15, 3
	s_or_b32 s14, s26, 1
	s_ashr_i32 s15, s14, 31
	s_lshl_b64 s[14:15], s[14:15], 12
	s_add_u32 s16, s50, s14
	s_addc_u32 s17, s51, s15
	v_writelane_b32 v247, s16, 4
	s_nop 1
	v_writelane_b32 v247, s17, 5
	s_or_b32 s16, s26, 2
	s_ashr_i32 s17, s16, 31
	s_lshl_b64 s[16:17], s[16:17], 12
	s_add_u32 s18, s50, s16
	s_addc_u32 s19, s51, s17
	v_writelane_b32 v247, s18, 6
	s_nop 1
	v_writelane_b32 v247, s19, 7
	s_or_b32 s18, s26, 3
	s_ashr_i32 s19, s18, 31
	s_lshl_b64 s[18:19], s[18:19], 12
	s_add_u32 s20, s50, s18
	s_addc_u32 s21, s51, s19
	v_writelane_b32 v247, s20, 8
	s_nop 1
	v_writelane_b32 v247, s21, 9
	s_or_b32 s20, s26, 4
	s_ashr_i32 s21, s20, 31
	s_lshl_b64 s[20:21], s[20:21], 12
	s_add_u32 s22, s50, s20
	s_addc_u32 s23, s51, s21
	v_writelane_b32 v247, s22, 10
	s_nop 1
	v_writelane_b32 v247, s23, 11
	s_or_b32 s22, s26, 5
	s_ashr_i32 s23, s22, 31
	s_lshl_b64 s[22:23], s[22:23], 12
	s_add_u32 s24, s50, s22
	s_addc_u32 s25, s51, s23
	v_writelane_b32 v247, s24, 12
	s_nop 1
	v_writelane_b32 v247, s25, 13
	s_or_b32 s24, s26, 6
	s_ashr_i32 s25, s24, 31
	s_lshl_b64 s[24:25], s[24:25], 12
	s_add_u32 s52, s50, s24
	s_addc_u32 s53, s51, s25
	v_writelane_b32 v247, s52, 14
	s_or_b32 s26, s26, 7
	s_ashr_i32 s27, s26, 31
	v_writelane_b32 v247, s53, 15
	v_writelane_b32 v247, s8, 16
	s_lshl_b64 s[26:27], s[26:27], 12
	s_add_u32 s52, s50, s26
	v_writelane_b32 v247, s9, 17
	v_writelane_b32 v247, s50, 18
	s_addc_u32 s53, s51, s27
	s_add_u32 s12, s42, s12
	v_writelane_b32 v247, s51, 19
	v_writelane_b32 v247, s52, 20
	s_addc_u32 s13, s43, s13
	s_nop 0
	v_writelane_b32 v247, s53, 21
	v_writelane_b32 v247, s12, 22
	s_nop 1
	v_writelane_b32 v247, s13, 23
	s_add_u32 s12, s42, s14
	s_addc_u32 s13, s43, s15
	v_writelane_b32 v247, s12, 24
	s_nop 1
	v_writelane_b32 v247, s13, 25
	s_add_u32 s12, s42, s16
	s_addc_u32 s13, s43, s17
	v_writelane_b32 v247, s12, 26
	s_nop 1
	v_writelane_b32 v247, s13, 27
	s_add_u32 s12, s42, s18
	s_addc_u32 s13, s43, s19
	v_writelane_b32 v247, s12, 28
	s_nop 1
	v_writelane_b32 v247, s13, 29
	s_add_u32 s12, s42, s20
	s_addc_u32 s13, s43, s21
	v_writelane_b32 v247, s12, 30
	s_nop 1
	v_writelane_b32 v247, s13, 31
	s_add_u32 s12, s42, s22
	s_addc_u32 s13, s43, s23
	v_writelane_b32 v247, s12, 32
	s_nop 1
	v_writelane_b32 v247, s13, 33
	s_add_u32 s12, s42, s24
	s_addc_u32 s13, s43, s25
	v_writelane_b32 v247, s12, 34
	s_nop 1
	v_writelane_b32 v247, s13, 35
	s_add_u32 s12, s42, s26
	v_writelane_b32 v250, s42, 17
	s_addc_u32 s13, s43, s27
	v_writelane_b32 v247, s12, 36
	s_cmpk_lt_i32 s30, 0x500
	v_writelane_b32 v250, s43, 18
	v_writelane_b32 v247, s13, 37
	s_cselect_b64 s[12:13], -1, 0
	v_writelane_b32 v247, s12, 38
	s_lshl_b32 s8, s46, 5
	s_and_b32 s8, s8, 0x60
	v_writelane_b32 v247, s13, 39
	v_writelane_b32 v247, s8, 40
	v_cmp_eq_u32_e64 s[12:13], 0, v0
	v_readfirstlane_b32 s8, v1
	s_cmp_lt_i32 s4, 0
	v_writelane_b32 v247, s12, 41
	v_writelane_b32 v250, s38, 58
	s_nop 0
	v_writelane_b32 v247, s13, 42
	v_writelane_b32 v247, s8, 43
	v_readfirstlane_b32 s8, v2
	s_cselect_b32 s12, s11, s31
	s_cselect_b32 s13, 41, 40
	v_writelane_b32 v247, s8, 44
	v_readfirstlane_b32 s8, v3
	v_writelane_b32 v250, s39, 59
	s_nop 0
	v_writelane_b32 v247, s8, 45
	v_readfirstlane_b32 s8, v4
	s_nop 1
	v_writelane_b32 v247, s8, 46
	s_movk_i32 s8, 0xb5
	s_cselect_b32 s8, s8, 0xb4
	s_mul_i32 s8, s4, s8
	v_writelane_b32 v247, s11, 47
	s_movk_i32 s11, 0xa1
	s_cselect_b32 s11, s11, 0xa0
	s_add_i32 s8, s8, s3
	s_mul_hi_i32 s14, s8, 0x38e38e39
	s_lshr_b32 s15, s14, 31
	s_ashr_i32 s14, s14, 6
	s_add_i32 s14, s14, s15
	s_mul_i32 s15, s14, 0x120
	s_sub_i32 s15, s8, s15
	s_bfe_u32 s8, s15, 0x3001c
	s_add_i32 s16, s15, s8
	s_sext_i32_i16 s17, s16
	s_and_b32 s16, s16, 0xfff8
	s_sub_i32 s15, s15, s16
	s_lshl_b32 s14, s14, 3
	s_sext_i32_i16 s15, s15
	s_add_i32 s18, s14, s15
	s_ashr_i32 s14, s17, 3
	v_writelane_b32 v247, s14, 48
	s_lshr_b32 s8, s17, 3
	v_writelane_b32 v247, s5, 49
	s_mul_hi_i32 s5, s6, 0x9000
	s_cmpk_gt_i32 s9, 0x9f
	v_writelane_b32 v247, s5, 50
	s_mul_i32 s5, s4, s13
	s_cselect_b32 s14, s10, s0
	s_add_i32 s5, s5, s3
	s_ashr_i32 s9, s5, 31
	s_lshr_b32 s9, s9, 26
	s_add_i32 s9, s5, s9
	s_ashr_i32 s10, s9, 6
	s_and_b32 s9, s9, 0xffc0
	s_sub_i32 s5, s5, s9
	s_bfe_i32 s9, s5, 0x80000
	s_bfe_u32 s9, s9, 0x3000c
	s_ashr_i32 s15, s14, 31
	s_add_i32 s9, s5, s9
	s_lshl_b64 s[14:15], s[14:15], 12
	s_lshl_b32 s13, s10, 3
	s_bfe_i32 s10, s9, 0x80000
	s_and_b32 s9, s9, 0xf8
	v_writelane_b32 v247, s14, 51
	s_sub_i32 s5, s5, s9
	s_sext_i32_i8 s5, s5
	v_writelane_b32 v247, s15, 52
	s_sext_i32_i16 s14, s10
	s_add_i32 s16, s13, s5
	s_ashr_i32 s5, s14, 3
	s_lshr_b32 s10, s14, 3
	v_writelane_b32 v247, s5, 53
	s_mov_b32 s14, s16
	s_ashr_i32 s17, s16, 31
	v_writelane_b32 v247, s14, 54
	s_mul_i32 s5, s12, s4
	s_mul_i32 s4, s4, s11
	v_writelane_b32 v247, s15, 55
	s_lshl_b64 s[14:15], s[16:17], 20
	s_bfe_i64 s[16:17], s[10:11], 0x100000
	s_lshl_b64 s[16:17], s[16:17], 20
	s_add_u32 s14, s64, s14
	v_writelane_b32 v247, s16, 56
	s_addc_u32 s15, s65, s15
	s_nop 0
	v_writelane_b32 v247, s17, 57
	s_add_u32 s16, s14, 0x80000
	v_writelane_b32 v247, s14, 58
	s_addc_u32 s17, s15, 0
	s_add_i32 s10, s5, s3
	s_add_i32 s3, s4, s3
	s_ashr_i32 s4, s3, 31
	s_lshr_b32 s4, s4, 24
	s_add_i32 s4, s3, s4
	s_ashr_i32 s5, s10, 31
	s_ashr_i32 s11, s4, 8
	s_and_b32 s4, s4, 0xff00
	s_lshr_b32 s5, s5, 26
	s_sub_i32 s3, s3, s4
	s_add_i32 s12, s10, s5
	s_sext_i32_i16 s4, s3
	s_ashr_i32 s5, s12, 6
	s_andn2_b32 s12, s12, 63
	s_bfe_u32 s4, s4, 0x3001c
	s_sub_i32 s10, s10, s12
	s_add_i32 s12, s3, s4
	s_sext_i32_i16 s13, s12
	s_and_b32 s12, s12, 0xfff8
	s_sub_i32 s3, s3, s12
	s_lshl_b32 s11, s11, 3
	s_sext_i32_i16 s3, s3
	v_writelane_b32 v247, s15, 59
	s_add_i32 s14, s11, s3
	v_writelane_b32 v247, s16, 60
	s_lshl_b32 s5, s5, 3
	s_mov_b32 s12, s14
	v_writelane_b32 v247, s17, 61
	s_sub_i32 s9, s31, s5
	s_lshr_b32 s4, s13, 3
	s_ashr_i32 s3, s13, 3
	s_ashr_i32 s15, s14, 31
	v_writelane_b32 v246, s12, 0
	v_writelane_b32 v247, s31, 62
	s_min_i32 s9, s9, 8
	v_writelane_b32 v246, s13, 1
	s_lshl_b64 s[12:13], s[14:15], 20
	s_bfe_i64 s[14:15], s[4:5], 0x100000
	v_writelane_b32 v247, s3, 63
	s_lshl_b64 s[14:15], s[14:15], 20
	v_readlane_b32 s16, v250, 61
	s_sext_i32_i8 s3, s9
	v_writelane_b32 v246, s14, 2
	v_readlane_b32 s17, v250, 62
	s_add_u32 s12, s16, s12
	v_cvt_f32_i32_e32 v2, s3
	v_writelane_b32 v246, s15, 3
	s_addc_u32 s13, s17, s13
	s_add_u32 s14, s12, 0x80000
	v_writelane_b32 v246, s12, 4
	s_addc_u32 s15, s13, 0
	v_cvt_f32_i32_e32 v1, s10
	v_writelane_b32 v246, s13, 5
	v_writelane_b32 v246, s14, 6
	v_rcp_iflag_f32_e32 v3, v2
	s_ashr_i32 s19, s18, 31
	v_writelane_b32 v246, s15, 7
	s_mov_b32 s4, s18
	s_bfe_i64 s[14:15], s[8:9], 0x100000
	v_writelane_b32 v246, s4, 8
	s_lshl_b64 s[12:13], s[18:19], 20
	s_lshl_b64 s[14:15], s[14:15], 20
	v_writelane_b32 v246, s5, 9
	s_add_u32 s12, s16, s12
	v_writelane_b32 v246, s14, 10
	s_addc_u32 s13, s17, s13
	v_mul_f32_e32 v3, v1, v3
	v_writelane_b32 v246, s15, 11
	s_add_u32 s14, s12, 0x80000
	v_trunc_f32_e32 v3, v3
	v_writelane_b32 v246, s12, 12
	s_addc_u32 s15, s13, 0
	s_xor_b32 s4, s10, s3
	v_fma_f32 v1, -v3, v2, v1
	v_cvt_i32_f32_e32 v3, v3
	s_ashr_i32 s4, s4, 30
	v_writelane_b32 v246, s13, 13
	s_or_b32 s4, s4, 1
	v_cmp_ge_f32_e64 s[12:13], |v1|, |v2|
	s_and_b64 s[12:13], s[12:13], exec
	s_cselect_b32 s3, s4, 0
	v_readfirstlane_b32 s4, v3
	v_writelane_b32 v246, s14, 14
	s_add_i32 s4, s4, s3
	s_sext_i32_i8 s3, s4
	v_writelane_b32 v246, s15, 15
	v_writelane_b32 v246, s3, 16
	s_mul_i32 s3, s4, s9
	s_sub_i32 s3, s10, s3
	s_sext_i32_i8 s3, s3
	s_add_i32 s10, s5, s3
	s_bfe_i64 s[4:5], s[4:5], 0x80000
	s_lshl_b64 s[12:13], s[4:5], 20
	s_ashr_i32 s11, s10, 31
	v_writelane_b32 v246, s12, 17
	s_lshl_b64 s[8:9], s[10:11], 20
	s_add_u32 s8, s40, s8
	v_writelane_b32 v246, s13, 18
	v_writelane_b32 v246, s40, 19
	s_addc_u32 s9, s41, s9
	s_add_u32 s12, s8, 0x80000
	v_writelane_b32 v246, s41, 20
	v_writelane_b32 v246, s8, 21
	s_addc_u32 s13, s9, 0
	s_lshl_b64 s[4:5], s[4:5], 22
	v_writelane_b32 v246, s9, 22
	v_writelane_b32 v246, s12, 23
	s_mov_b32 s8, s10
	v_writelane_b32 v250, s35, 55
	v_writelane_b32 v246, s13, 24
	v_writelane_b32 v246, s8, 25
	v_mbcnt_lo_u32_b32 v1, -1, 0
	s_movk_i32 s31, 0xffc0
	v_writelane_b32 v246, s9, 26
	v_writelane_b32 v246, s4, 27
	s_lshl_b64 s[8:9], s[10:11], 22
	v_mov_b32_e32 v3, 0
	v_writelane_b32 v246, s5, 28
	s_add_u32 s4, s48, s8
	v_writelane_b32 v246, s48, 29
	s_addc_u32 s5, s49, s9
	s_add_u32 s8, s4, 0x200000
	v_writelane_b32 v246, s49, 30
	v_writelane_b32 v246, s4, 31
	s_addc_u32 s9, s5, 0
	v_mbcnt_hi_u32_b32 v204, -1, v1
	v_writelane_b32 v246, s5, 32
	v_writelane_b32 v246, s8, 33
	s_lshl_b64 s[4:5], s[28:29], 14
	s_add_u32 s3, s4, 0xc0010
	v_writelane_b32 v246, s9, 34
	v_readlane_b32 s8, v249, 11
	s_addc_u32 s24, s5, 0
	v_readlane_b32 s12, v249, 15
	v_readlane_b32 s13, v249, 16
	s_add_u32 s4, s12, s3
	s_addc_u32 s5, s13, s24
	v_writelane_b32 v246, s4, 35
	v_readlane_b32 s10, v249, 13
	v_readlane_b32 s11, v249, 14
	v_writelane_b32 v246, s5, 36
	s_lshl_b64 s[4:5], s[28:29], 13
	s_add_u32 s4, s44, s4
	s_addc_u32 s5, s45, s5
	s_add_u32 s10, s4, 0x1d460008
	s_addc_u32 s11, s5, 0
	v_readlane_b32 s14, v249, 17
	v_writelane_b32 v246, s10, 37
	v_readlane_b32 s15, v249, 18
	v_readlane_b32 s22, v249, 25
	v_writelane_b32 v246, s11, 38
	s_add_u32 s10, s14, s3
	s_addc_u32 s11, s15, s24
	v_writelane_b32 v246, s10, 39
	s_add_u32 s4, s4, 0x1dc60008
	s_addc_u32 s5, s5, 0
	v_writelane_b32 v246, s11, 40
	v_writelane_b32 v246, s4, 41
	s_add_i32 s3, s2, 0x1f80
	s_lshl_b64 s[0:1], s[0:1], 2
	v_writelane_b32 v246, s5, 42
	v_writelane_b32 v246, s3, 43
	s_lshl_b32 s3, s46, 2
	v_writelane_b32 v246, s3, 44
	s_lshl_b32 s3, s34, 2
	v_writelane_b32 v246, s3, 45
	s_add_i32 s3, s2, 0x2880
	v_writelane_b32 v246, s3, 46
	s_addk_i32 s2, 0x100
	v_writelane_b32 v246, s2, 47
	s_lshl_b32 s2, s30, 8
	s_add_i32 s2, s2, s35
	v_writelane_b32 v246, s2, 48
	s_lshl_b32 s2, s36, 16
	v_writelane_b32 v246, s2, 49
	v_writelane_b32 v246, s36, 50
	s_lshl_b32 s2, s36, 12
	v_writelane_b32 v246, s2, 51
	v_writelane_b32 v246, s0, 52
	s_lshl_b32 s2, s34, 3
	v_writelane_b32 v250, s2, 47
	v_writelane_b32 v246, s1, 53
	s_lshl_b64 s[0:1], s[6:7], 1
	v_writelane_b32 v246, s0, 54
	s_movk_i32 s5, 0x7fff
	s_movk_i32 s22, 0x2000
	s_mov_b32 s30, 0x3e38aa3b
	v_writelane_b32 v246, s1, 55
	s_mov_b32 s0, 0
	v_readlane_b32 s9, v249, 12
	v_readlane_b32 s16, v249, 19
	v_readlane_b32 s17, v249, 20
	v_readlane_b32 s18, v249, 21
	v_readlane_b32 s19, v249, 22
	v_readlane_b32 s20, v249, 23
	v_readlane_b32 s21, v249, 24
	v_readlane_b32 s23, v249, 26
	v_writelane_b32 v246, s0, 56
	s_branch .LBB0_392
.LBB0_389:
	s_or_b64 exec, exec, s[6:7]
	s_waitcnt vmcnt(0)
	buffer_inv sc1
	s_waitcnt vmcnt(0)
.LBB0_390:
	s_or_b64 exec, exec, s[0:1]
	s_waitcnt lgkmcnt(0)
	s_barrier

.LBB0_661:
	s_or_b64 exec, exec, s[6:7]
	s_and_saveexec_b64 s[6:7], s[8:9]
	s_cbranch_execz .LBB0_663
	v_readlane_b32 s2, v249, 0
	v_readlane_b32 s3, v249, 1
	s_nop 0
	s_add_u32 s2, s2, 0x6400
	s_addc_u32 s3, s3, 0
	s_nop 4
	global_atomic_add v3, v202, s[2:3]
	global_atomic_add v3, v202, s[2:3] offset:256
	global_atomic_add v3, v202, s[2:3] offset:512
	global_atomic_add v3, v202, s[2:3] offset:768
	global_atomic_add v3, v202, s[2:3] offset:1024
	global_atomic_add v3, v202, s[2:3] offset:1280
	global_atomic_add v3, v202, s[2:3] offset:1536
	global_atomic_add v3, v202, s[2:3] offset:1792
	global_atomic_add v3, v202, s[2:3] offset:2048
	global_atomic_add v3, v202, s[2:3] offset:2304
	global_atomic_add v3, v202, s[2:3] offset:2560
	global_atomic_add v3, v202, s[2:3] offset:2816
	global_atomic_add v3, v202, s[2:3] offset:3072
	global_atomic_add v3, v202, s[2:3] offset:3328
	global_atomic_add v3, v202, s[2:3] offset:3584
	global_atomic_add v3, v202, s[2:3] offset:3840
	global_atomic_add v[4:5], v202, off
.LBB0_663:
	s_or_b64 exec, exec, s[6:7]
	s_waitcnt vmcnt(0)
	buffer_inv sc1
	s_waitcnt vmcnt(0)
.LBB0_664:
	s_or_b64 exec, exec, s[0:1]
	s_waitcnt lgkmcnt(0)
	s_barrier

.LBB0_903:
	s_or_b64 exec, exec, s[6:7]
	s_waitcnt vmcnt(0)
	buffer_inv sc1
	s_waitcnt vmcnt(0)
.LBB0_904:
	s_or_b64 exec, exec, s[0:1]
	s_waitcnt lgkmcnt(0)
	s_barrier

.LBB0_1069:
	s_or_b64 exec, exec, s[6:7]
	s_waitcnt vmcnt(0)
	buffer_inv sc1
	s_waitcnt vmcnt(0)
.LBB0_1070:
	s_or_b64 exec, exec, s[0:1]
	s_waitcnt lgkmcnt(0)
	s_barrier

.LBB0_1142:
	s_or_b64 exec, exec, s[6:7]
	s_waitcnt vmcnt(0)
	buffer_inv sc1
	s_waitcnt vmcnt(0)
.LBB0_1143:
	s_or_b64 exec, exec, s[0:1]
	s_waitcnt lgkmcnt(0)
	s_barrier

.LBB0_1206:
	s_or_b64 exec, exec, s[8:9]
	s_and_saveexec_b64 s[8:9], s[10:11]
	s_cbranch_execz .LBB0_1208
	v_readlane_b32 s2, v249, 0
	v_readlane_b32 s3, v249, 1
	s_nop 0
	s_add_u32 s2, s2, 0x6400
	s_addc_u32 s3, s3, 0
	s_nop 4
	global_atomic_add v3, v202, s[2:3]
	global_atomic_add v3, v202, s[2:3] offset:256
	global_atomic_add v3, v202, s[2:3] offset:512
	global_atomic_add v3, v202, s[2:3] offset:768
	global_atomic_add v3, v202, s[2:3] offset:1024
	global_atomic_add v3, v202, s[2:3] offset:1280
	global_atomic_add v3, v202, s[2:3] offset:1536
	global_atomic_add v3, v202, s[2:3] offset:1792
	global_atomic_add v3, v202, s[2:3] offset:2048
	global_atomic_add v3, v202, s[2:3] offset:2304
	global_atomic_add v3, v202, s[2:3] offset:2560
	global_atomic_add v3, v202, s[2:3] offset:2816
	global_atomic_add v3, v202, s[2:3] offset:3072
	global_atomic_add v3, v202, s[2:3] offset:3328
	global_atomic_add v3, v202, s[2:3] offset:3584
	global_atomic_add v3, v202, s[2:3] offset:3840
	global_atomic_add v[4:5], v202, off
.LBB0_1208:
	s_or_b64 exec, exec, s[8:9]
	s_waitcnt vmcnt(0)
	buffer_inv sc1
	s_waitcnt vmcnt(0)
.LBB0_1209:
	s_or_b64 exec, exec, s[6:7]
	s_waitcnt lgkmcnt(0)
	s_barrier

.LBB0_1277:
	s_or_b64 exec, exec, s[8:9]
	s_waitcnt vmcnt(0)
	buffer_inv sc1
	s_waitcnt vmcnt(0)
.LBB0_1278:
	s_or_b64 exec, exec, s[6:7]
	s_waitcnt lgkmcnt(0)
	s_barrier

.LBB0_1350:
	s_or_b64 exec, exec, s[8:9]
	s_waitcnt vmcnt(0)
	buffer_inv sc1
	s_waitcnt vmcnt(0)
.LBB0_1351:
	s_or_b64 exec, exec, s[6:7]
	s_waitcnt lgkmcnt(0)
	s_barrier

.LBB0_1421:
	v_readlane_b32 s2, v249, 0
	v_readlane_b32 s3, v249, 1
	s_nop 0
	s_add_u32 s2, s2, 0x6400
	s_addc_u32 s3, s3, 0
	s_nop 4
	global_atomic_add v3, v202, s[2:3]
	global_atomic_add v3, v202, s[2:3] offset:256
	global_atomic_add v3, v202, s[2:3] offset:512
	global_atomic_add v3, v202, s[2:3] offset:768
	global_atomic_add v3, v202, s[2:3] offset:1024
	global_atomic_add v3, v202, s[2:3] offset:1280
	global_atomic_add v3, v202, s[2:3] offset:1536
	global_atomic_add v3, v202, s[2:3] offset:1792
	global_atomic_add v3, v202, s[2:3] offset:2048
	global_atomic_add v3, v202, s[2:3] offset:2304
	global_atomic_add v3, v202, s[2:3] offset:2560
	global_atomic_add v3, v202, s[2:3] offset:2816
	global_atomic_add v3, v202, s[2:3] offset:3072
	global_atomic_add v3, v202, s[2:3] offset:3328
	global_atomic_add v3, v202, s[2:3] offset:3584
	global_atomic_add v3, v202, s[2:3] offset:3840
	global_atomic_add v[4:5], v202, off
	s_getpc_b64 s[98:99]
